# no grid barrier between the forget-scan phase and attention: scan workgroups publish completion (barrier-style release), C units acquire lazily before their first use
# speedup vs baseline: 1.0134x; 1.0092x over previous
; #define LAS __attribute__((address_space(3)))
; DI void attn_phase(const Params& P, char* shm) {
;     ...
;     LAS unsigned* su = (LAS unsigned*)((att::lds_cptr)shm + OFF_UNIT);
;     if (tid >= 256) __builtin_amdgcn_s_setprio(1);
;     const unsigned xcd = (unsigned)__builtin_amdgcn_s_getreg((3 << 11) | 20) & 7u;
;     for (unsigned k = 0; k < 8; ++k) {
;         const unsigned q = (xcd + k) & 7u; unsigned* cnt = P.counter + 16 * q;
.LBB0_316:
	v_writelane_b32 v255, 0, 61
	s_nop 0
	s_mov_b32 s0, 0x40000000
	v_writelane_b32 v255, s0, 62
	s_nop 0
	v_writelane_b32 v255, 0, 60
	s_nop 0
	v_readlane_b32 s0, v255, 29
	s_add_i32 s0, s1, s0
	v_writelane_b32 v255, s1, 45
	s_and_b32 s0, s0, 7
	s_lshl_b32 s1, s0, 6
	v_readlane_b32 s2, v255, 25
	s_add_u32 s42, s2, s1
	v_readlane_b32 s1, v255, 26
	s_mul_i32 s41, s0, 0x180
	s_addc_u32 s43, s1, 0
	v_writelane_b32 v255, s41, 46
	v_writelane_b32 v255, s42, 47
	s_nop 1
	v_writelane_b32 v255, s43, 48
	s_branch .LBB0_320

; DI int opaque_tid() { int t = threadIdx.x; asm volatile("" : "+v"(t)); return t; }
; #define ATT_WAIT_BAR() asm volatile("s_waitcnt vmcnt(0) lgkmcnt(0)\n\ts_barrier" ::: "memory")
; template <int KIND> DI void attn_unit(const Params& P, int b, int h, int qb, char* shm, float lam, bool dry = false) {
;     ...
;     const int tid = opaque_tid(), lane = tid & 63, r32 = lane & 31, hi = lane >> 5; const int wid = __builtin_amdgcn_readfirstlane(tid >> 6);
;     const long rowbase = (long)b * SEQ;
;     int qrow0, qoff, T_lo, T_hi, wt_lo, wt_hi; const int m = wid >> 2;
;     if (KIND == 0) { qrow0 = qb * 128 + 32 * (wid & 3); qoff = h * 128 + m * 64; T_lo = 0; T_hi = 2 * qb + 1; wt_lo = 0; wt_hi = 2 * qb + ((wid & 3) >> 1); }
;     else if (KIND == 1) { qrow0 = qb * 256 + 32 * wid; qoff = 512 + h * 64; const int cq = 4 * qb + (wid >> 1); T_lo = 4 * qb - 8 < 0 ? 0 : 4 * qb - 8; T_hi = 4 * qb + 3; wt_lo = cq - 8 < 0 ? 0 : cq - 8; wt_hi = cq; }
;     else { qrow0 = qb * 256 + 32 * wid; qoff = 1024 + h * 64; T_lo = 0; T_hi = 4 * qb + 3; wt_lo = 0; wt_hi = 4 * qb + (wid >> 1); }
;     const int kvoff = (KIND == 0) ? h * 128 : qoff;
;     const unsigned lds0 = (unsigned)(uintptr_t)shm;
;     const lds_cptr shm3 = (lds_cptr)shm;
;     const int hk = kvoff >> 6, vb0 = kvoff >> 5;
;     const bf16_t* ksrc = P.Kp + ((size_t)(b * 24 + hk) * 256) * 4096 + wid * 512 + lane * 8;
;     const bf16_t* vsrc0 = P.Vp + ((size_t)(b * 48 + vb0 + (wid >> 2)) * 256) * 2048 + (wid & 3) * 512 + lane * 8;
;     const bf16_t* kxsrc = P.KX + ((size_t)(b * 8 + h) * SEQ + lane) * 8;
; DI void attn_phase(const Params& P, char* shm) {
;     ...
;             const unsigned e = P.order[q * 384 + ui]; const int kind = e >> 28, b = (e >> 24) & 15, h = (e >> 16) & 255, qb = e & 0xffff;
;     ...
;             { const int reps = (kind == 0) ? PROBE_REP_A : (kind == 2 ? PROBE_REP_C : 1);
;               for (int rep = 1; rep < reps; ++rep) { if (kind == 0) attn_unit<0>(P, b, h, qb, shm, lam, P.lam_init > -1.0f); else attn_unit<2>(P, b, h, qb, shm, lam, P.lam_init > -1.0f); ATT_WAIT_BAR(); } }
;     ...
;             if (kind == 0) attn_unit<0>(P, b, h, qb, shm, lam);
;             else if (kind == 1) attn_unit<1>(P, b, h, qb, shm, lam);
;             else attn_unit<2>(P, b, h, qb, shm, lam);
.Ldq_dec:
	v_readfirstlane_b32 s0, v166
	v_cmp_lt_u32_e32 vcc, s1, v166
	s_bfe_u32 s2, s0, 0x40018
	s_bfe_u32 s28, s0, 0x80010
	s_and_b32 s3, s0, 0xffff
	s_mov_b64 s[0:1], -1
	s_cbranch_vccz .LBB0_377
	s_brev_b32 s0, -8
	v_cmp_lt_u32_e32 vcc, s0, v166
	s_lshl_b32 s14, s2, 14
	s_lshl_b32 s16, s3, 8
	s_lshl_b32 s15, s28, 6
	s_lshl_b32 s33, s3, 2
	s_mov_b64 s[0:1], -1
	s_mul_i32 s10, s2, 24
	s_cbranch_vccz .LBB0_365
	v_readlane_b32 s0, v255, 60
	s_cmp_lg_u32 s0, 0
	s_cbranch_scc1 .Lsm_ok
	v_readlane_b32 s0, v255, 5
	v_readlane_b32 s1, v255, 6
	v_readlane_b32 s4, v254, 60
	s_lshl_b32 s4, s4, 9
	s_add_u32 s0, s0, s4
	s_addc_u32 s1, s1, 0
.Lsm_spin:
	global_load_dword v0, v2, s[0:1] offset:4 sc1
	s_waitcnt vmcnt(0)
	v_readfirstlane_b32 s4, v0
	s_cmp_ge_u32 s4, 16
	s_cbranch_scc1 .Lsm_got
	s_sleep 8
	s_branch .Lsm_spin
.Lsm_got:
	buffer_inv sc1
	v_writelane_b32 v255, 1, 60
	s_nop 0
.Lsm_ok:
	s_add_i32 s0, s15, 0x400
	v_mov_b32_e32 v53, v236
	s_lshr_b32 s1, s0, 6
	s_add_i32 s1, s1, s10
	v_readfirstlane_b32 s9, v53
	s_ashr_i32 s8, s9, 6
	s_or_b32 s7, s33, 3
	s_lshr_b32 s4, s0, 5
	s_lshl_b32 s0, s1, 21
	s_add_u32 s5, s24, s0
	s_addc_u32 s6, s25, 0
	s_lshl_b32 s0, s8, 9
	s_ashr_i32 s1, s0, 31
	s_lshl_b64 s[0:1], s[0:1], 1
	v_and_b32_e32 v52, 63, v53
	s_add_u32 s0, s5, s0
	s_addc_u32 s1, s6, s1
	v_lshlrev_b32_e32 v0, 4, v52
	v_mov_b32_e32 v1, v2
	v_lshl_add_u64 v[156:157], s[0:1], 0, v[0:1]
	s_mul_i32 s0, s2, 48
	s_add_i32 s0, s4, s0
	s_ashr_i32 s1, s9, 8
	s_add_i32 s0, s0, s1
	s_ashr_i32 s1, s0, 31
	s_lshl_b64 s[0:1], s[0:1], 20
	s_add_u32 s0, s26, s0
	s_addc_u32 s1, s27, s1
	s_lshl_b32 s41, s8, 10
	s_and_b32 s4, s41, 0xc00
	s_add_u32 s0, s0, s4
	s_addc_u32 s1, s1, 0
	s_lshl_b32 s11, s2, 3
	s_add_i32 s11, s11, s28
	s_lshl_b32 s6, s11, 14
	v_lshl_add_u64 v[158:159], s[0:1], 0, v[0:1]
	v_or_b32_e32 v0, s6, v52
	v_readlane_b32 s0, v255, 19
	s_lshl_b32 s20, s7, 13
	v_lshlrev_b32_e32 v0, 4, v0
	v_readlane_b32 s1, v255, 20
	s_cmp_lg_u32 0, -1
	s_nop 0
	v_lshl_add_u64 v[160:161], s[0:1], 0, v[0:1]
	s_cselect_b32 s0, 0, 0
	s_add_i32 s0, s41, s0
	v_lshl_add_u64 v[0:1], v[156:157], 0, s[20:21]
	s_mov_b32 s1, m0
	s_mov_b32 m0, s0
	s_nop 0
	global_load_lds_dwordx4 v[0:1], off
	s_mov_b32 m0, s1
	s_lshl_b32 s20, s7, 12
	s_addk_i32 s0, 0x4000
	s_cmp_lt_u32 s9, 64
	v_lshl_add_u64 v[0:1], v[158:159], 0, s[20:21]
	s_mov_b32 s1, m0
	s_mov_b32 m0, s0
	s_nop 0
	global_load_lds_dwordx4 v[0:1], off
	s_mov_b32 m0, s1
	s_cselect_b64 s[4:5], -1, 0
	s_cmp_gt_u32 s9, 63
	s_cselect_b64 s[0:1], -1, 0
	s_and_b64 vcc, exec, s[0:1]
	s_cbranch_vccnz .LBB0_329
	s_lshl_b32 s20, s7, 10
	s_cmp_lg_u32 0, -1
	s_cselect_b32 s7, 0, 0
	v_lshl_add_u64 v[0:1], v[160:161], 0, s[20:21]
	s_add_i32 s7, s7, 0x8000
	s_mov_b32 s10, m0
	s_mov_b32 m0, s7
	s_nop 0
	global_load_lds_dwordx4 v[0:1], off
	s_mov_b32 m0, s10

; __device__ __forceinline__ void xcd_barrier(const XcdBarrier& b) {
;     asm volatile("s_waitcnt vmcnt(0)" ::: "memory");
;     __syncthreads();
;     if (threadIdx.x == 0) {
;         unsigned* bar = b.bar;
;         __builtin_amdgcn_s_waitcnt(0);
;         unsigned nloc = b.st[0], nx = b.st[1];
;         if (nloc == 0u) { xcd_barrier_complete(bar, b.x, nloc, nx); b.st[0] = nloc; b.st[1] = nx; }
; __global__ void __launch_bounds__(NWAVES * 64, 2) fwd_kernel(Args a) {
;     ...
;         if (ph + 1 < a.ph_hi) { if (ph == 0) cg::this_grid().sync(); else xcd_barrier(xbar); }
.Lsm_skip:
	s_waitcnt vmcnt(0) lgkmcnt(0)
	s_barrier
	v_readlane_b32 s0, v252, 43
	v_readlane_b32 s1, v252, 44
	v_readlane_b32 s2, v252, 3
	v_readlane_b32 s3, v252, 4
	s_and_b64 s[0:1], s[0:1], s[2:3]
	s_and_saveexec_b64 s[2:3], s[0:1]
	s_cbranch_execz .Lsm_norel
	buffer_wbl2 sc1
	s_waitcnt vmcnt(0) lgkmcnt(0)
	s_cmp_eq_u32 s64, 11
	s_cselect_b32 s0, 0x204, 4
	s_add_u32 s0, s66, s0
	s_addc_u32 s1, s67, 0
	v_mov_b32_e32 v0, 1
	global_atomic_add v2, v0, s[0:1]
	s_waitcnt vmcnt(0)
.Lsm_norel:
	s_or_b64 exec, exec, s[2:3]
	s_branch .LBB0_9
.LBB0_793:
	s_add_i32 s64, s64, 1
	s_cmp_ge_i32 s64, s65
	s_mov_b64 s[0:1], -1
	s_cbranch_scc1 .LBB0_10
	s_cmp_eq_u32 s64, 3
	s_cbranch_scc1 .Lsm_skip
	s_cmp_eq_u32 s64, 11
	s_cbranch_scc1 .Lsm_skip
	v_readlane_b32 s0, v254, 55
	v_readlane_b32 s1, v254, 56
	s_and_b64 vcc, exec, s[0:1]
	s_waitcnt vmcnt(0)
	s_waitcnt vmcnt(0) lgkmcnt(0)
	s_barrier
	s_mov_b64 s[0:1], exec
	v_readlane_b32 s2, v252, 3
	v_readlane_b32 s3, v252, 4
	s_and_b64 s[2:3], s[0:1], s[2:3]
	s_mov_b64 exec, s[2:3]
	s_cbranch_execz .LBB0_849
	v_readlane_b32 s2, v254, 28
	s_waitcnt vmcnt(0) expcnt(0) lgkmcnt(0)
	s_nop 0
	v_mov_b32_e32 v0, s2
	ds_read_b32 v3, v0
	v_readlane_b32 s2, v254, 29
	s_waitcnt lgkmcnt(0)
	v_cmp_ne_u32_e32 vcc, 0, v3
	v_mov_b32_e32 v0, s2
	ds_read_b32 v0, v0
	s_cbranch_vccnz .LBB0_813
	v_readlane_b32 s4, v252, 5
	v_readlane_b32 s5, v252, 6
	s_load_dwordx2 s[2:3], s[4:5], 0x4
	v_readlane_b32 s4, v254, 27
	s_mov_b32 s9, 1
	s_waitcnt lgkmcnt(0)
	s_mul_i32 s8, s2, s4
	s_mul_i32 s8, s8, s3
	s_branch .LBB0_799
